# 32x32x16 attention loop with K/V^T LDS row stride 288 instead of 272 (bank-conflict sensitivity of the 32-row fragment reads)
# baseline (speedup 1.0000x reference)
.LBB0_747:
	s_and_b64 vcc, exec, s[10:11]
	s_cbranch_vccz .LBB0_751
	v_mov_b32_e32 v10, v232
	s_load_dwordx8 s[52:59], s[44:45], 0x60
	v_and_b32_e32 v181, 63, v10
	v_readlane_b32 s10, v255, 20
	v_mov_b32_e32 v3, v0
	s_load_dwordx2 s[42:43], s[44:45], 0xb0
	v_or_b32_e32 v2, s10, v181
	v_lshlrev_b64 v[2:3], 2, v[2:3]
	s_waitcnt lgkmcnt(0)
	v_lshl_add_u64 v[4:5], s[52:53], 0, v[2:3]
	global_load_dword v11, v[4:5], off
	v_lshl_add_u64 v[4:5], s[54:55], 0, v[2:3]
	global_load_dword v12, v[4:5], off
	v_lshl_add_u64 v[4:5], s[56:57], 0, v[2:3]
	v_lshl_add_u64 v[2:3], s[58:59], 0, v[2:3]
	global_load_dword v13, v[4:5], off
	global_load_dword v14, v[2:3], off
	s_add_i32 s6, s37, s48
	s_lshl_b32 s14, s36, 7
	s_lshl_b32 s30, s36, 8
	v_readlane_b32 s11, v255, 21
	s_add_u32 s10, s42, s47
	s_addc_u32 s11, s43, s46
	s_add_u32 s36, s10, s30
	s_addc_u32 s37, s11, 0
	s_lshl_b32 s10, s27, 10
	s_or_b32 s10, s14, s10
	s_mul_hi_i32 s11, s10, 0x2200
	s_mulk_i32 s10, 0x2200
	v_ashrrev_i32_e32 v50, 4, v10
	s_add_u32 s10, s42, s10
	v_ashrrev_i32_e32 v51, 31, v50
	v_and_b32_e32 v177, 15, v10
	s_addc_u32 s11, s43, s11
	v_lshlrev_b64 v[52:53], 11, v[50:51]
	s_add_u32 s40, s10, 0xe010000
	v_lshl_add_u64 v[2:3], s[36:37], 0, v[52:53]
	v_lshlrev_b32_e32 v124, 4, v177
	v_mov_b32_e32 v125, v0
	s_addc_u32 s41, s11, 0
	v_lshl_add_u64 v[2:3], v[2:3], 0, v[124:125]
	s_mov_b32 s15, 0x16810000
	v_mov_b64_e32 v[4:5], s[40:41]
	s_movk_i32 s35, 0x2200
	v_add_co_u32_e32 v6, vcc, s15, v2
	v_mad_i64_i32 v[4:5], s[36:37], v50, s35, v[4:5]
	s_nop 0
	v_addc_co_u32_e32 v7, vcc, 0, v3, vcc
	s_mov_b32 s15, 0x16820000
	v_lshl_add_u64 v[4:5], v[4:5], 0, v[124:125]
	global_load_dwordx4 v[18:21], v[6:7], off
	global_load_dwordx4 v[22:25], v[4:5], off
	v_add_co_u32_e32 v6, vcc, s15, v2
	s_mov_b32 s15, 0x44000
	s_nop 0
	v_addc_co_u32_e32 v7, vcc, 0, v3, vcc
	v_add_co_u32_e32 v8, vcc, s15, v4
	s_mov_b32 s15, 0x16830000
	s_nop 0
	v_addc_co_u32_e32 v9, vcc, 0, v5, vcc
	global_load_dwordx4 v[26:29], v[6:7], off
	global_load_dwordx4 v[30:33], v[8:9], off
	v_add_co_u32_e32 v6, vcc, s15, v2
	s_mov_b32 s15, 0x88000
	s_nop 0
	v_addc_co_u32_e32 v7, vcc, 0, v3, vcc
	v_add_co_u32_e32 v8, vcc, s15, v4
	s_mov_b32 s15, 0x16840000
	s_nop 0
	v_addc_co_u32_e32 v9, vcc, 0, v5, vcc
	v_add_co_u32_e32 v2, vcc, s15, v2
	s_mov_b32 s15, 0xcc000
	s_nop 0
	v_addc_co_u32_e32 v3, vcc, 0, v3, vcc
	v_add_co_u32_e32 v4, vcc, s15, v4
	global_load_dwordx4 v[34:37], v[6:7], off
	global_load_dwordx4 v[38:41], v[8:9], off
	v_addc_co_u32_e32 v5, vcc, 0, v5, vcc
	global_load_dwordx4 v[42:45], v[2:3], off
	global_load_dwordx4 v[46:49], v[4:5], off
	v_ashrrev_i32_e32 v4, 2, v10
	v_and_b32_e32 v4, 0xffffffe0, v4
	v_add_u32_e32 v180, s6, v4
	v_ashrrev_i32_e32 v182, 6, v10
	v_and_b32_e32 v179, 1, v182
	v_mov_b32_e32 v55, v0
	v_lshlrev_b32_e32 v54, 7, v179
	s_waitcnt vmcnt(10)
	v_mul_f32_e32 v2, v11, v12
	ds_bpermute_b32 v2, v1, v2
	v_and_b32_e32 v56, 48, v10
	v_mov_b32_e32 v57, v0
	s_waitcnt vmcnt(8)
	v_mul_f32_e32 v3, v13, v14
	ds_bpermute_b32 v3, v1, v3
	s_waitcnt lgkmcnt(1)
	v_fmac_f32_e32 v2, v11, v12
	ds_bpermute_b32 v5, v176, v2
	s_mov_b32 s6, 0x14610000
	s_mov_b64 s[36:37], 0x14610000
	s_waitcnt lgkmcnt(1)
	v_fmac_f32_e32 v3, v13, v14
	ds_bpermute_b32 v6, v176, v3
	s_waitcnt lgkmcnt(1)
	v_add_f32_e32 v4, v2, v5
	v_and_b32_e32 v2, 31, v223
	v_or_b32_e32 v2, v180, v2
	v_bfe_u32 v178, v10, 4, 2
	v_lshlrev_b32_e32 v51, 1, v50
	s_waitcnt lgkmcnt(0)
	v_add_f32_e32 v5, v3, v6
	ds_bpermute_b32 v6, v175, v4
	ds_bpermute_b32 v7, v175, v5
	v_ashrrev_i32_e32 v3, 31, v2
	v_lshlrev_b64 v[2:3], 11, v[2:3]
	v_lshl_add_u64 v[2:3], s[42:43], 0, v[2:3]
	s_waitcnt lgkmcnt(1)
	v_add_f32_e32 v4, v4, v6
	s_waitcnt lgkmcnt(0)
	v_add_f32_e32 v5, v5, v7
	ds_bpermute_b32 v6, v174, v4
	ds_bpermute_b32 v7, v174, v5
	v_lshl_add_u64 v[2:3], v[2:3], 0, s[30:31]
	v_lshl_add_u64 v[2:3], v[2:3], 0, v[54:55]
	v_lshrrev_b32_e32 v55, 1, v50
	s_waitcnt lgkmcnt(1)
	v_add_f32_e32 v132, v4, v6
	s_waitcnt lgkmcnt(0)
	v_add_f32_e32 v133, v5, v7
	v_and_b32_e32 v56, 32, v232
	v_lshrrev_b32_e32 v56, 1, v56
	v_lshl_add_u64 v[6:7], v[2:3], 0, v[56:57]
	v_add_co_u32_e32 v4, vcc, s6, v6
	s_mov_b32 s6, 0x14610020
	s_nop 0
	v_addc_co_u32_e32 v5, vcc, 0, v7, vcc
	v_lshl_add_u64 v[2:3], v[6:7], 0, s[36:37]
	v_add_co_u32_e32 v6, vcc, s6, v6
	global_load_dwordx4 v[10:13], v[4:5], off
	s_nop 0
	global_load_dwordx4 v[2:5], v[2:3], off offset:64
	v_addc_co_u32_e32 v7, vcc, 0, v7, vcc
	global_load_dwordx4 v[14:17], v[6:7], off
	s_nop 0
	global_load_dwordx4 v[6:9], v[6:7], off offset:64
	v_and_b32_e32 v51, 8, v51
	v_and_b32_e32 v55, 4, v55
	v_and_b32_e32 v57, 0xffffff3, v50
	v_or3_b32 v51, v57, v51, v55
	s_movk_i32 s6, 0x120
	v_mul_lo_u32 v55, v50, s6
	v_mad_u64_u32 v[126:127], s[36:37], v51, s6, v[124:125]
	s_mov_b32 s6, 0x12000
	v_add3_u32 v127, v55, v124, s6
	v_add_u32_e32 v51, 0, v126
	v_add_u32_e32 v55, 0, v127
	s_waitcnt vmcnt(11)
	ds_write_b128 v51, v[18:21]
	s_waitcnt vmcnt(10)
	ds_write_b128 v55, v[22:25]
	s_waitcnt vmcnt(9)
	ds_write_b128 v51, v[26:29] offset:9216
	s_waitcnt vmcnt(8)
	ds_write_b128 v55, v[30:33] offset:9216
	s_waitcnt vmcnt(7)
	ds_write_b128 v51, v[34:37] offset:18432
	s_waitcnt vmcnt(6)
	ds_write_b128 v55, v[38:41] offset:18432
	s_waitcnt vmcnt(5)
	ds_write_b128 v51, v[42:45] offset:27648
	s_waitcnt vmcnt(4)
	ds_write_b128 v55, v[46:49] offset:27648
	s_add_i32 s6, 0, 0x12000
	v_mul_u32_u24_e32 v19, 0x120, v177
	v_add3_u32 v183, s6, v56, v19
	s_lshl_b32 s6, s26, 3
	s_and_b32 s6, s6, 0x700
	ds_bpermute_b32 v134, v173, v132
	ds_bpermute_b32 v135, v173, v133
	s_add_u32 s6, s42, s6
	v_add_u32_e32 v18, 0, v54
	s_addc_u32 s18, s43, 0
	v_add3_u32 v137, v18, v56, v19
	s_add_u32 s26, s6, s47
	v_mov_b64_e32 v[18:19], s[10:11]
	s_addc_u32 s27, s18, s46
	v_mad_i64_i32 v[130:131], s[10:11], v50, s35, v[18:19]
	v_mov_b32_e32 v18, 0
	s_mov_b32 s15, 0
	v_lshl_add_u64 v[128:129], s[26:27], 0, v[52:53]
	v_mov_b32_e32 v19, v18
	v_mov_b32_e32 v20, v18
	v_mov_b32_e32 v21, v18
	v_mov_b32_e32 v22, v18
	v_mov_b32_e32 v23, v18
	v_mov_b32_e32 v24, v18
	v_mov_b32_e32 v25, v18
	v_mov_b32_e32 v26, v18
	v_mov_b32_e32 v27, v18
	v_mov_b32_e32 v28, v18
	v_mov_b32_e32 v29, v18
	v_mov_b32_e32 v30, v18
	v_mov_b32_e32 v31, v18
	v_mov_b32_e32 v32, v18
	v_mov_b32_e32 v33, v18
	v_mov_b32_e32 v38, v18
	v_mov_b32_e32 v39, v18
	v_mov_b32_e32 v40, v18
	v_mov_b32_e32 v41, v18
	v_mov_b32_e32 v46, v18
	v_mov_b32_e32 v47, v18
	v_mov_b32_e32 v48, v18
	v_mov_b32_e32 v49, v18
	v_mov_b32_e32 v62, v18
	v_mov_b32_e32 v63, v18
	v_mov_b32_e32 v64, v18
	v_mov_b32_e32 v65, v18
	v_mov_b32_e32 v74, v18
	v_mov_b32_e32 v75, v18
	v_mov_b32_e32 v76, v18
	v_mov_b32_e32 v77, v18
	v_mov_b32_e32 v34, v18
	v_mov_b32_e32 v35, v18
	v_mov_b32_e32 v36, v18
	v_mov_b32_e32 v37, v18
	v_mov_b32_e32 v42, v18
	v_mov_b32_e32 v43, v18
	v_mov_b32_e32 v44, v18
	v_mov_b32_e32 v45, v18
	v_mov_b32_e32 v50, v18
	v_mov_b32_e32 v51, v18
	v_mov_b32_e32 v52, v18
	v_mov_b32_e32 v53, v18
	v_mov_b32_e32 v54, v18
	v_mov_b32_e32 v55, v18
	v_mov_b32_e32 v56, v18
	v_mov_b32_e32 v57, v18
	v_mov_b32_e32 v58, v18
	v_mov_b32_e32 v59, v18
	v_mov_b32_e32 v60, v18
	v_mov_b32_e32 v61, v18
	v_mov_b32_e32 v66, v18
	v_mov_b32_e32 v67, v18
	v_mov_b32_e32 v68, v18
	v_mov_b32_e32 v69, v18
	v_mov_b32_e32 v70, v18
	v_mov_b32_e32 v71, v18
	v_mov_b32_e32 v72, v18
	v_mov_b32_e32 v73, v18
	v_mov_b32_e32 v78, v18
	v_mov_b32_e32 v79, v18
	v_mov_b32_e32 v80, v18
	v_mov_b32_e32 v81, v18
	v_mov_b32_e32 v122, v18
	v_mov_b32_e32 v123, v18
	s_mov_b32 s11, 0xe054000
	s_mov_b32 s18, 0x16870000
	s_mov_b32 s26, 0xe098000
	s_mov_b32 s27, 0x16880000
	s_mov_b32 s30, 0xe0dc000
	s_mov_b64 s[36:37], 0x40000
	s_waitcnt lgkmcnt(0)
	s_barrier
	s_waitcnt vmcnt(0) lgkmcnt(0)
	v_writelane_b32 v175, s64, 0
	v_writelane_b32 v175, s65, 1
	v_writelane_b32 v175, s66, 2
	v_writelane_b32 v175, s67, 3
	v_writelane_b32 v175, s68, 4
	v_writelane_b32 v175, s69, 5
	v_writelane_b32 v175, s70, 6
	v_writelane_b32 v175, s71, 7
	v_writelane_b32 v175, s72, 8
	v_writelane_b32 v175, s73, 9
	v_writelane_b32 v175, s74, 10
	v_writelane_b32 v175, s75, 11
	v_writelane_b32 v175, s76, 12
	v_writelane_b32 v175, s77, 13
	v_writelane_b32 v175, s78, 14
	v_writelane_b32 v175, s79, 15
	v_lshl_add_u64 v[138:139], v[128:129], 0, v[124:125]
	v_lshl_add_u64 v[140:141], v[130:131], 0, v[124:125]
	s_nop 1
	v_readfirstlane_b32 s64, v138
	v_readfirstlane_b32 s65, v139
	v_readfirstlane_b32 s72, v140
	v_readfirstlane_b32 s73, v141
	s_nop 3
	v_subrev_u32_e32 v124, s64, v138
	v_subrev_u32_e32 v125, s72, v140
	s_add_u32 s66, s64, s97
	s_addc_u32 s67, s65, 0
	s_add_u32 s68, s64, s18
	s_addc_u32 s69, s65, 0
	s_add_u32 s70, s64, s27
	s_addc_u32 s71, s65, 0
	s_add_u32 s64, s64, s96
	s_addc_u32 s65, s65, 0
	s_add_u32 s74, s72, s11
	s_addc_u32 s75, s73, 0
	s_add_u32 s74, s74, 0x100
	s_addc_u32 s75, s75, 0
	s_add_u32 s76, s72, s26
	s_addc_u32 s77, s73, 0
	s_add_u32 s76, s76, 0x100
	s_addc_u32 s77, s77, 0
	s_add_u32 s78, s72, s30
	s_addc_u32 s79, s73, 0
	s_add_u32 s78, s78, 0x100
	s_addc_u32 s79, s79, 0
	s_add_u32 s72, s72, s91
	s_addc_u32 s73, s73, 0
	s_add_u32 s72, s72, 0x100
	s_addc_u32 s73, s73, 0
	v_and_b32_e32 v137, 31, v223
	v_mul_u32_u24_e32 v137, 0x120, v137
	v_lshrrev_b32_e32 v183, 5, v223
	v_lshl_add_u32 v137, v183, 4, v137
	v_add_u32_e32 v183, 0x12000, v137
	v_lshl_add_u32 v137, v179, 7, v137
	s_mov_b32 s15, 0
	s_nop 4
	.p2align 6
.Lattn_nf_loop:
	s_and_b32 s10, s15, 1
	s_mul_i32 s6, s10, 0x9000
	v_add_u32_e32 v136, s6, v137
	v_add_u32_e32 v170, s6, v183
	s_sub_u32 s10, 0x9000, s6
	ds_read_b128 v[98:101], v136 offset:0
	ds_read_b128 v[102:105], v136 offset:32
	ds_read_b128 v[106:109], v136 offset:64
	ds_read_b128 v[110:113], v136 offset:96
	v_add_u32_e32 v171, s10, v126
	v_add_u32_e32 v173, s10, v127
	global_load_dwordx4 v[82:85], v124, s[64:65]
	global_load_dwordx4 v[86:89], v124, s[66:67]
	global_load_dwordx4 v[90:93], v124, s[68:69]
	global_load_dwordx4 v[94:97], v124, s[70:71]
	v_add_u32_e32 v124, s36, v124
	s_waitcnt lgkmcnt(3)
	v_mfma_f32_32x32x16_bf16 v[138:153], v[98:101], v[10:13], 0
	ds_read_b128 v[98:101], v136 offset:9216
	s_waitcnt lgkmcnt(3)
	v_mfma_f32_32x32x16_bf16 v[138:153], v[102:105], v[14:17], v[138:153]
	ds_read_b128 v[102:105], v136 offset:9248
	s_waitcnt lgkmcnt(3)
	v_mfma_f32_32x32x16_bf16 v[138:153], v[106:109], v[2:5], v[138:153]
	ds_read_b128 v[106:109], v136 offset:9280
	s_waitcnt lgkmcnt(3)
	v_mfma_f32_32x32x16_bf16 v[138:153], v[110:113], v[6:9], v[138:153]
	ds_read_b128 v[110:113], v136 offset:9312
	ds_read_b128 v[128:131], v170 offset:0
	ds_read_b128 v[184:187], v170 offset:9216
	ds_read_b128 v[188:191], v170 offset:18432
	ds_read_b128 v[192:195], v170 offset:27648
	s_waitcnt lgkmcnt(7)
	v_mfma_f32_32x32x16_bf16 v[154:169], v[98:101], v[10:13], 0
	ds_read_b128 v[98:101], v136 offset:18432
	s_nop 3
	v_exp_f32_e32 v138, v138
	v_exp_f32_e32 v139, v139
	v_exp_f32_e32 v140, v140
	v_exp_f32_e32 v141, v141
	v_exp_f32_e32 v142, v142
	v_exp_f32_e32 v143, v143
	s_waitcnt lgkmcnt(7)
	v_mfma_f32_32x32x16_bf16 v[154:169], v[102:105], v[14:17], v[154:169]
	ds_read_b128 v[102:105], v136 offset:18464
	v_exp_f32_e32 v144, v144
	v_exp_f32_e32 v145, v145
	v_add_f32_e32 v122, v138, v122
	v_add_f32_e32 v122, v139, v122
	v_add_f32_e32 v122, v140, v122
	v_add_f32_e32 v122, v141, v122
	v_add_f32_e32 v122, v142, v122
	v_add_f32_e32 v122, v143, v122
	v_add_f32_e32 v122, v144, v122
	v_add_f32_e32 v122, v145, v122
	v_cvt_pk_bf16_f32 v114, v138, v139
	v_cvt_pk_bf16_f32 v115, v140, v141
	v_cvt_pk_bf16_f32 v116, v142, v143
	v_cvt_pk_bf16_f32 v117, v144, v145
	ds_read_b128 v[196:199], v170 offset:32
	ds_read_b128 v[216:219], v170 offset:9248
	ds_read_b128 v[200:203], v170 offset:18464
	ds_read_b128 v[204:207], v170 offset:27680
	s_waitcnt lgkmcnt(11)
	v_mfma_f32_32x32x16_bf16 v[154:169], v[106:109], v[2:5], v[154:169]
	ds_read_b128 v[106:109], v136 offset:18496
	v_exp_f32_e32 v146, v146
	v_exp_f32_e32 v147, v147
	s_waitcnt lgkmcnt(11)
	v_mfma_f32_32x32x16_bf16 v[154:169], v[110:113], v[6:9], v[154:169]
	ds_read_b128 v[110:113], v136 offset:18528
	v_exp_f32_e32 v148, v148
	v_exp_f32_e32 v149, v149
	s_waitcnt lgkmcnt(11)
	v_mfma_f32_32x32x16_bf16 v[18:33], v[128:131], v[114:117], v[18:33]
	v_exp_f32_e32 v150, v150
	v_exp_f32_e32 v151, v151
	s_waitcnt lgkmcnt(10)
	v_mfma_f32_32x32x16_bf16 v[34:49], v[184:187], v[114:117], v[34:49]
	v_exp_f32_e32 v152, v152
	v_exp_f32_e32 v153, v153
	s_waitcnt lgkmcnt(9)
	v_mfma_f32_32x32x16_bf16 v[50:65], v[188:191], v[114:117], v[50:65]
	v_add_f32_e32 v122, v146, v122
	v_add_f32_e32 v122, v147, v122
	v_add_f32_e32 v122, v148, v122
	v_add_f32_e32 v122, v149, v122
	s_waitcnt lgkmcnt(8)
	v_mfma_f32_32x32x16_bf16 v[66:81], v[192:195], v[114:117], v[66:81]
	v_add_f32_e32 v122, v150, v122
	v_add_f32_e32 v122, v151, v122
	v_add_f32_e32 v122, v152, v122
	v_add_f32_e32 v122, v153, v122
	v_cvt_pk_bf16_f32 v118, v146, v147
	v_cvt_pk_bf16_f32 v119, v148, v149
	v_cvt_pk_bf16_f32 v120, v150, v151
	v_cvt_pk_bf16_f32 v121, v152, v153
	ds_read_b128 v[128:131], v170 offset:64
	ds_read_b128 v[184:187], v170 offset:9280
	ds_read_b128 v[188:191], v170 offset:18496
	ds_read_b128 v[192:195], v170 offset:27712
	s_waitcnt lgkmcnt(11)
	v_mfma_f32_32x32x16_bf16 v[138:153], v[98:101], v[10:13], 0
	ds_read_b128 v[98:101], v136 offset:27648
	v_exp_f32_e32 v154, v154
	v_exp_f32_e32 v155, v155
	s_waitcnt lgkmcnt(11)
	v_mfma_f32_32x32x16_bf16 v[138:153], v[102:105], v[14:17], v[138:153]
	ds_read_b128 v[102:105], v136 offset:27680
	v_exp_f32_e32 v156, v156
	v_exp_f32_e32 v157, v157
	s_waitcnt lgkmcnt(11)
	v_mfma_f32_32x32x16_bf16 v[18:33], v[196:199], v[118:121], v[18:33]
	v_exp_f32_e32 v158, v158
	v_exp_f32_e32 v159, v159
	s_waitcnt lgkmcnt(10)
	v_mfma_f32_32x32x16_bf16 v[34:49], v[216:219], v[118:121], v[34:49]
	v_exp_f32_e32 v160, v160
	v_exp_f32_e32 v161, v161
	s_waitcnt lgkmcnt(9)
	v_mfma_f32_32x32x16_bf16 v[50:65], v[200:203], v[118:121], v[50:65]
	v_add_f32_e32 v122, v154, v122
	v_add_f32_e32 v122, v155, v122
	v_add_f32_e32 v122, v156, v122
	v_add_f32_e32 v122, v157, v122
	s_waitcnt lgkmcnt(8)
	v_mfma_f32_32x32x16_bf16 v[66:81], v[204:207], v[118:121], v[66:81]
	v_add_f32_e32 v122, v158, v122
	v_add_f32_e32 v122, v159, v122
	v_add_f32_e32 v122, v160, v122
	v_add_f32_e32 v122, v161, v122
	v_cvt_pk_bf16_f32 v114, v154, v155
	v_cvt_pk_bf16_f32 v115, v156, v157
	v_cvt_pk_bf16_f32 v116, v158, v159
	v_cvt_pk_bf16_f32 v117, v160, v161
	ds_read_b128 v[196:199], v170 offset:96
	ds_read_b128 v[216:219], v170 offset:9312
	ds_read_b128 v[200:203], v170 offset:18528
	ds_read_b128 v[204:207], v170 offset:27744
	s_waitcnt lgkmcnt(11)
	v_mfma_f32_32x32x16_bf16 v[138:153], v[106:109], v[2:5], v[138:153]
	ds_read_b128 v[106:109], v136 offset:27712
	v_exp_f32_e32 v162, v162
	v_exp_f32_e32 v163, v163
	s_waitcnt lgkmcnt(11)
	v_mfma_f32_32x32x16_bf16 v[138:153], v[110:113], v[6:9], v[138:153]
	ds_read_b128 v[110:113], v136 offset:27744
	v_exp_f32_e32 v164, v164
	v_exp_f32_e32 v165, v165
	s_waitcnt lgkmcnt(11)
	v_mfma_f32_32x32x16_bf16 v[18:33], v[128:131], v[114:117], v[18:33]
	v_exp_f32_e32 v166, v166
	v_exp_f32_e32 v167, v167
	s_waitcnt lgkmcnt(10)
	v_mfma_f32_32x32x16_bf16 v[34:49], v[184:187], v[114:117], v[34:49]
	v_exp_f32_e32 v168, v168
	v_exp_f32_e32 v169, v169
	s_waitcnt lgkmcnt(9)
	v_mfma_f32_32x32x16_bf16 v[50:65], v[188:191], v[114:117], v[50:65]
	v_add_f32_e32 v122, v162, v122
	v_add_f32_e32 v122, v163, v122
	v_add_f32_e32 v122, v164, v122
	v_add_f32_e32 v122, v165, v122
	s_waitcnt lgkmcnt(8)
	v_mfma_f32_32x32x16_bf16 v[66:81], v[192:195], v[114:117], v[66:81]
	v_add_f32_e32 v122, v166, v122
	v_add_f32_e32 v122, v167, v122
	v_add_f32_e32 v122, v168, v122
	v_add_f32_e32 v122, v169, v122
	v_cvt_pk_bf16_f32 v118, v162, v163
	v_cvt_pk_bf16_f32 v119, v164, v165
	v_cvt_pk_bf16_f32 v120, v166, v167
	v_cvt_pk_bf16_f32 v121, v168, v169
	ds_read_b128 v[128:131], v170 offset:128
	ds_read_b128 v[184:187], v170 offset:9344
	ds_read_b128 v[188:191], v170 offset:18560
	ds_read_b128 v[192:195], v170 offset:27776
	s_waitcnt lgkmcnt(11)
	v_mfma_f32_32x32x16_bf16 v[154:169], v[98:101], v[10:13], 0
	v_exp_f32_e32 v138, v138
	s_waitcnt lgkmcnt(10)
	v_mfma_f32_32x32x16_bf16 v[154:169], v[102:105], v[14:17], v[154:169]
	v_exp_f32_e32 v139, v139
	v_exp_f32_e32 v140, v140
	s_waitcnt lgkmcnt(9)
	v_mfma_f32_32x32x16_bf16 v[18:33], v[196:199], v[118:121], v[18:33]
	v_exp_f32_e32 v141, v141
	v_exp_f32_e32 v142, v142
	s_waitcnt vmcnt(3)
	ds_write_b128 v171, v[82:85] offset:0
	s_waitcnt vmcnt(2)
	ds_write_b128 v171, v[86:89] offset:9216
	s_waitcnt vmcnt(1)
	ds_write_b128 v171, v[90:93] offset:18432
	s_waitcnt vmcnt(0)
	ds_write_b128 v171, v[94:97] offset:27648
	v_exp_f32_e32 v143, v143
	s_waitcnt lgkmcnt(12)
	v_mfma_f32_32x32x16_bf16 v[34:49], v[216:219], v[118:121], v[34:49]
	v_exp_f32_e32 v144, v144
	v_exp_f32_e32 v145, v145
	v_add_f32_e32 v122, v138, v122
	s_waitcnt lgkmcnt(11)
	v_mfma_f32_32x32x16_bf16 v[50:65], v[200:203], v[118:121], v[50:65]
	v_add_f32_e32 v122, v139, v122
	v_add_f32_e32 v122, v140, v122
	v_add_f32_e32 v122, v141, v122
	s_waitcnt lgkmcnt(10)
	v_mfma_f32_32x32x16_bf16 v[66:81], v[204:207], v[118:121], v[66:81]
	v_add_f32_e32 v122, v142, v122
	v_add_f32_e32 v122, v143, v122
	v_add_f32_e32 v122, v144, v122
	v_add_f32_e32 v122, v145, v122
	v_cvt_pk_bf16_f32 v114, v138, v139
	v_cvt_pk_bf16_f32 v115, v140, v141
	v_cvt_pk_bf16_f32 v116, v142, v143
	v_cvt_pk_bf16_f32 v117, v144, v145
	ds_read_b128 v[196:199], v170 offset:160
	ds_read_b128 v[216:219], v170 offset:9376
	ds_read_b128 v[200:203], v170 offset:18592
	ds_read_b128 v[204:207], v170 offset:27808
	s_waitcnt lgkmcnt(13)
	v_mfma_f32_32x32x16_bf16 v[154:169], v[106:109], v[2:5], v[154:169]
	v_exp_f32_e32 v146, v146
	s_waitcnt lgkmcnt(12)
	v_mfma_f32_32x32x16_bf16 v[154:169], v[110:113], v[6:9], v[154:169]
	v_exp_f32_e32 v147, v147
	v_exp_f32_e32 v148, v148
	s_waitcnt lgkmcnt(11)
	v_mfma_f32_32x32x16_bf16 v[18:33], v[128:131], v[114:117], v[18:33]
	v_exp_f32_e32 v149, v149
	v_exp_f32_e32 v150, v150
	global_load_dwordx4 v[82:85], v125, s[72:73]
	global_load_dwordx4 v[86:89], v125, s[74:75]
	global_load_dwordx4 v[90:93], v125, s[76:77]
	global_load_dwordx4 v[94:97], v125, s[78:79]
	v_add_u32_e32 v125, s38, v125
	v_exp_f32_e32 v151, v151
	s_waitcnt lgkmcnt(10)
	v_mfma_f32_32x32x16_bf16 v[34:49], v[184:187], v[114:117], v[34:49]
	v_exp_f32_e32 v152, v152
	v_exp_f32_e32 v153, v153
	v_add_f32_e32 v122, v146, v122
	s_waitcnt lgkmcnt(9)
	v_mfma_f32_32x32x16_bf16 v[50:65], v[188:191], v[114:117], v[50:65]
	v_add_f32_e32 v122, v147, v122
	v_add_f32_e32 v122, v148, v122
	v_add_f32_e32 v122, v149, v122
	s_waitcnt lgkmcnt(8)
	v_mfma_f32_32x32x16_bf16 v[66:81], v[192:195], v[114:117], v[66:81]
	v_add_f32_e32 v122, v150, v122
	v_add_f32_e32 v122, v151, v122
	v_add_f32_e32 v122, v152, v122
	v_add_f32_e32 v122, v153, v122
	v_cvt_pk_bf16_f32 v118, v146, v147
	v_cvt_pk_bf16_f32 v119, v148, v149
	v_cvt_pk_bf16_f32 v120, v150, v151
	v_cvt_pk_bf16_f32 v121, v152, v153
	ds_read_b128 v[128:131], v170 offset:192
	ds_read_b128 v[184:187], v170 offset:9408
	ds_read_b128 v[188:191], v170 offset:18624
	ds_read_b128 v[192:195], v170 offset:27840
	s_waitcnt lgkmcnt(7)
	v_mfma_f32_32x32x16_bf16 v[18:33], v[196:199], v[118:121], v[18:33]
	v_exp_f32_e32 v154, v154
	v_exp_f32_e32 v155, v155
	v_exp_f32_e32 v156, v156
	s_waitcnt lgkmcnt(6)
	v_mfma_f32_32x32x16_bf16 v[34:49], v[216:219], v[118:121], v[34:49]
	v_exp_f32_e32 v157, v157
	v_exp_f32_e32 v158, v158
	v_exp_f32_e32 v159, v159
	s_waitcnt lgkmcnt(5)
	v_mfma_f32_32x32x16_bf16 v[50:65], v[200:203], v[118:121], v[50:65]
	v_exp_f32_e32 v160, v160
	v_exp_f32_e32 v161, v161
	v_add_f32_e32 v122, v154, v122
	v_add_f32_e32 v122, v155, v122
	s_waitcnt lgkmcnt(4)
	v_mfma_f32_32x32x16_bf16 v[66:81], v[204:207], v[118:121], v[66:81]
	v_add_f32_e32 v122, v156, v122
	v_add_f32_e32 v122, v157, v122
	v_add_f32_e32 v122, v158, v122
	v_add_f32_e32 v122, v159, v122
	v_add_f32_e32 v122, v160, v122
	v_add_f32_e32 v122, v161, v122
	v_cvt_pk_bf16_f32 v114, v154, v155
	v_cvt_pk_bf16_f32 v115, v156, v157
	v_cvt_pk_bf16_f32 v116, v158, v159
	v_cvt_pk_bf16_f32 v117, v160, v161
	ds_read_b128 v[196:199], v170 offset:224
	ds_read_b128 v[216:219], v170 offset:9440
	ds_read_b128 v[200:203], v170 offset:18656
	ds_read_b128 v[204:207], v170 offset:27872
	s_waitcnt lgkmcnt(7)
	v_mfma_f32_32x32x16_bf16 v[18:33], v[128:131], v[114:117], v[18:33]
	v_exp_f32_e32 v162, v162
	v_exp_f32_e32 v163, v163
	v_exp_f32_e32 v164, v164
	s_waitcnt lgkmcnt(6)
	v_mfma_f32_32x32x16_bf16 v[34:49], v[184:187], v[114:117], v[34:49]
	v_exp_f32_e32 v165, v165
	v_exp_f32_e32 v166, v166
	v_exp_f32_e32 v167, v167
	s_waitcnt lgkmcnt(5)
	v_mfma_f32_32x32x16_bf16 v[50:65], v[188:191], v[114:117], v[50:65]
	v_exp_f32_e32 v168, v168
	v_exp_f32_e32 v169, v169
	v_add_f32_e32 v122, v162, v122
	v_add_f32_e32 v122, v163, v122
	s_waitcnt lgkmcnt(4)
	v_mfma_f32_32x32x16_bf16 v[66:81], v[192:195], v[114:117], v[66:81]
	v_add_f32_e32 v122, v164, v122
	v_add_f32_e32 v122, v165, v122
	v_add_f32_e32 v122, v166, v122
	v_add_f32_e32 v122, v167, v122
	v_add_f32_e32 v122, v168, v122
	v_add_f32_e32 v122, v169, v122
	v_cvt_pk_bf16_f32 v118, v162, v163
	v_cvt_pk_bf16_f32 v119, v164, v165
	v_cvt_pk_bf16_f32 v120, v166, v167
	v_cvt_pk_bf16_f32 v121, v168, v169
	s_waitcnt lgkmcnt(3)
	s_nop 0
	v_mfma_f32_32x32x16_bf16 v[18:33], v[196:199], v[118:121], v[18:33]
	s_waitcnt lgkmcnt(2)
	v_mfma_f32_32x32x16_bf16 v[34:49], v[216:219], v[118:121], v[34:49]
	s_waitcnt vmcnt(3)
	ds_write_b128 v173, v[82:85] offset:0
	s_waitcnt vmcnt(2)
	ds_write_b128 v173, v[86:89] offset:9216
	s_waitcnt vmcnt(1)
	ds_write_b128 v173, v[90:93] offset:18432
	s_waitcnt vmcnt(0)
	ds_write_b128 v173, v[94:97] offset:27648
	s_waitcnt lgkmcnt(5)
	v_mfma_f32_32x32x16_bf16 v[50:65], v[200:203], v[118:121], v[50:65]
	s_waitcnt lgkmcnt(4)
	v_mfma_f32_32x32x16_bf16 v[66:81], v[204:207], v[118:121], v[66:81]
	s_waitcnt lgkmcnt(0)
	s_barrier
	s_add_i32 s15, s15, 1
	s_cmp_eq_u32 s15, 34
	s_cbranch_scc0 .Lattn_nf_loop
	v_readlane_b32 s64, v175, 0
	v_readlane_b32 s65, v175, 1
	v_readlane_b32 s66, v175, 2
	v_readlane_b32 s67, v175, 3
	v_readlane_b32 s68, v175, 4
	v_readlane_b32 s69, v175, 5
	v_readlane_b32 s70, v175, 6
	v_readlane_b32 s71, v175, 7
	v_readlane_b32 s72, v175, 8
	v_readlane_b32 s73, v175, 9
	v_readlane_b32 s74, v175, 10
	v_readlane_b32 s75, v175, 11
	v_readlane_b32 s76, v175, 12
	v_readlane_b32 s77, v175, 13
	v_readlane_b32 s78, v175, 14
	v_readlane_b32 s79, v175, 15
	s_nop 4
	v_add_f32_e32 v186, v132, v134
	v_add_f32_e32 v184, v133, v135
	ds_bpermute_b32 v187, v172, v186
	ds_bpermute_b32 v185, v172, v184
	s_mov_b32 s10, 0x3fb8aa3b
	s_mov_b32 s11, 0xc2ce8ed0
	s_mov_b32 s6, 0x42b17218
	v_cmp_eq_u32_e64 s[40:41], 0, v179
	s_lshl_b32 s30, s14, 1
	v_lshlrev_b32_e32 v196, 3, v178
	v_mov_b32_e32 v197, 0
	v_lshlrev_b32_e32 v198, 4, v179
	v_or3_b32 v198, v198, v177, v180
	v_ashrrev_i32_e32 v199, 31, v198
	v_lshlrev_b64 v[198:199], 11, v[198:199]
	s_mov_b64 s[100:101], 0x18a10000
	v_lshl_add_u64 v[198:199], s[42:43], 0, v[198:199]
	v_lshl_add_u64 v[198:199], v[198:199], 0, s[30:31]
	v_lshl_add_u64 v[198:199], v[198:199], 0, v[196:197]
	v_lshl_add_u64 v[198:199], v[198:199], 0, s[100:101]
	global_load_dwordx2 v[146:147], v[198:199], off
	global_load_dwordx2 v[148:149], v[198:199], off offset:32
	global_load_dwordx2 v[150:151], v[198:199], off offset:64
	global_load_dwordx2 v[152:153], v[198:199], off offset:96
	global_load_dwordx2 v[188:189], v[198:199], off offset:128
	global_load_dwordx2 v[190:191], v[198:199], off offset:160
	global_load_dwordx2 v[192:193], v[198:199], off offset:192
	global_load_dwordx2 v[194:195], v[198:199], off offset:224
	s_mov_b64 s[100:101], exec
	s_and_b64 exec, exec, s[4:5]
	s_cbranch_execz .Lpop_skip
	v_readlane_b32 s14, v255, 22
	v_readlane_b32 s15, v255, 23
	v_mov_b32_e32 v224, 1
	s_nop 4
	global_atomic_add v224, v0, v224, s[14:15] sc0
.Lpop_skip:
	s_mov_b64 exec, s[100:101]
	v_mov_b32_e32 v235, 1
	s_load_dwordx2 s[100:101], s[44:45], 0x80
	v_readlane_b32 s14, v255, 36
	v_readlane_b32 s15, v255, 37
	s_nop 3
	s_lshl_b64 s[14:15], s[14:15], 2
	s_waitcnt lgkmcnt(0)
	v_add_f32_e32 v84, v186, v187
	v_mul_f32_e32 v85, 0x3fb8aa3b, v84
	v_fma_f32 v86, v84, s10, -v85
	v_rndne_f32_e32 v87, v85
	v_fmac_f32_e32 v86, 0x32a5705f, v84
	v_sub_f32_e32 v85, v85, v87
	v_add_f32_e32 v85, v85, v86
	v_exp_f32_e32 v85, v85
	v_cvt_i32_f32_e32 v86, v87
	v_cmp_ngt_f32_e32 vcc, s11, v84
	s_nop 0
	v_ldexp_f32 v85, v85, v86
	s_nop 1
	v_cndmask_b32_e32 v85, 0, v85, vcc
	v_cmp_nlt_f32_e32 vcc, s6, v84
	s_nop 1
	v_cndmask_b32_e32 v88, v220, v85, vcc
	v_add_f32_e32 v84, v184, v185
	v_mul_f32_e32 v85, 0x3fb8aa3b, v84
	v_fma_f32 v86, v84, s10, -v85
	v_rndne_f32_e32 v87, v85
	v_fmac_f32_e32 v86, 0x32a5705f, v84
	v_sub_f32_e32 v85, v85, v87
	v_add_f32_e32 v85, v85, v86
	v_exp_f32_e32 v85, v85
	v_cvt_i32_f32_e32 v86, v87
	v_cmp_ngt_f32_e32 vcc, s11, v84
	s_nop 0
	v_ldexp_f32 v85, v85, v86
	s_nop 1
	v_cndmask_b32_e32 v85, 0, v85, vcc
	v_cmp_nlt_f32_e32 vcc, s6, v84
	s_nop 1
	v_cndmask_b32_e32 v89, v220, v85, vcc
	v_sub_f32_e32 v88, v88, v89
	v_add_f32_e32 v88, v236, v88
	s_nop 1
	v_cndmask_b32_e64 v88, -v88, 1.0, s[40:41]
	v_xor_b32_e32 v82, 32, v223
	v_lshlrev_b32_e32 v82, 2, v82
	ds_bpermute_b32 v83, v82, v122
	s_waitcnt lgkmcnt(0)
	v_add_f32_e32 v83, v122, v83
	v_div_scale_f32 v90, s[10:11], v83, v83, v88
	v_rcp_f32_e32 v91, v90
	s_nop 0
	v_fma_f32 v92, -v90, v91, 1.0
	v_fmac_f32_e32 v91, v92, v91
	v_div_scale_f32 v92, vcc, v88, v83, v88
	v_mul_f32_e32 v93, v92, v91
	v_fma_f32 v94, -v90, v93, v92
	v_fmac_f32_e32 v93, v94, v91
	v_fma_f32 v90, -v90, v93, v92
	s_nop 1
	v_div_fmas_f32 v90, v90, v91, v93
	v_div_fixup_f32 v96, v90, v83, v88
	v_and_b32_e32 v98, 31, v223
	v_mul_u32_u24_e32 v98, 528, v98
	v_lshrrev_b32_e32 v99, 5, v223
	v_lshl_add_u32 v98, v99, 4, v98
	s_movk_i32 s6, 0x4200
	v_mad_u32_u24 v98, v182, s6, v98
	v_pk_mul_f32 v[18:19], v[18:19], v[96:97] op_sel_hi:[1,0]
	v_pk_mul_f32 v[20:21], v[20:21], v[96:97] op_sel_hi:[1,0]
	v_pk_mul_f32 v[22:23], v[22:23], v[96:97] op_sel_hi:[1,0]
	v_pk_mul_f32 v[24:25], v[24:25], v[96:97] op_sel_hi:[1,0]
	v_pk_mul_f32 v[26:27], v[26:27], v[96:97] op_sel_hi:[1,0]
	v_pk_mul_f32 v[28:29], v[28:29], v[96:97] op_sel_hi:[1,0]
	v_pk_mul_f32 v[30:31], v[30:31], v[96:97] op_sel_hi:[1,0]
	v_pk_mul_f32 v[32:33], v[32:33], v[96:97] op_sel_hi:[1,0]
	ds_write_b128 v98, v[18:21] offset:0
	ds_write_b128 v98, v[22:25] offset:32
	ds_write_b128 v98, v[26:29] offset:64
	ds_write_b128 v98, v[30:33] offset:96
	v_pk_mul_f32 v[34:35], v[34:35], v[96:97] op_sel_hi:[1,0]
	v_pk_mul_f32 v[36:37], v[36:37], v[96:97] op_sel_hi:[1,0]
	v_pk_mul_f32 v[38:39], v[38:39], v[96:97] op_sel_hi:[1,0]
	v_pk_mul_f32 v[40:41], v[40:41], v[96:97] op_sel_hi:[1,0]
	v_pk_mul_f32 v[42:43], v[42:43], v[96:97] op_sel_hi:[1,0]
	v_pk_mul_f32 v[44:45], v[44:45], v[96:97] op_sel_hi:[1,0]
	v_pk_mul_f32 v[46:47], v[46:47], v[96:97] op_sel_hi:[1,0]
	v_pk_mul_f32 v[48:49], v[48:49], v[96:97] op_sel_hi:[1,0]
	ds_write_b128 v98, v[34:37] offset:128
	ds_write_b128 v98, v[38:41] offset:160
	ds_write_b128 v98, v[42:45] offset:192
	ds_write_b128 v98, v[46:49] offset:224
	s_waitcnt lgkmcnt(0)
	v_pk_mul_f32 v[50:51], v[50:51], v[96:97] op_sel_hi:[1,0]
	v_pk_mul_f32 v[52:53], v[52:53], v[96:97] op_sel_hi:[1,0]
	v_pk_mul_f32 v[54:55], v[54:55], v[96:97] op_sel_hi:[1,0]
	v_pk_mul_f32 v[56:57], v[56:57], v[96:97] op_sel_hi:[1,0]
	v_pk_mul_f32 v[58:59], v[58:59], v[96:97] op_sel_hi:[1,0]
	v_pk_mul_f32 v[60:61], v[60:61], v[96:97] op_sel_hi:[1,0]
	v_pk_mul_f32 v[62:63], v[62:63], v[96:97] op_sel_hi:[1,0]
	v_pk_mul_f32 v[64:65], v[64:65], v[96:97] op_sel_hi:[1,0]
	ds_write_b128 v98, v[50:53] offset:256
	ds_write_b128 v98, v[54:57] offset:288
	ds_write_b128 v98, v[58:61] offset:320
	ds_write_b128 v98, v[62:65] offset:352
	v_pk_mul_f32 v[66:67], v[66:67], v[96:97] op_sel_hi:[1,0]
	v_pk_mul_f32 v[68:69], v[68:69], v[96:97] op_sel_hi:[1,0]
	v_pk_mul_f32 v[70:71], v[70:71], v[96:97] op_sel_hi:[1,0]
	v_pk_mul_f32 v[72:73], v[72:73], v[96:97] op_sel_hi:[1,0]
	v_pk_mul_f32 v[74:75], v[74:75], v[96:97] op_sel_hi:[1,0]
	v_pk_mul_f32 v[76:77], v[76:77], v[96:97] op_sel_hi:[1,0]
	v_pk_mul_f32 v[78:79], v[78:79], v[96:97] op_sel_hi:[1,0]
	v_pk_mul_f32 v[80:81], v[80:81], v[96:97] op_sel_hi:[1,0]
	ds_write_b128 v98, v[66:69] offset:384
	ds_write_b128 v98, v[70:73] offset:416
	ds_write_b128 v98, v[74:77] offset:448
	ds_write_b128 v98, v[78:81] offset:480
	s_waitcnt lgkmcnt(0)
	s_barrier
	s_add_u32 s100, s100, s14
	s_addc_u32 s101, s101, s15
	v_lshlrev_b32_e32 v132, 4, v178
	global_load_dwordx4 v[100:103], v132, s[100:101]
	global_load_dwordx4 v[104:107], v132, s[100:101] offset:64
	global_load_dwordx4 v[108:111], v132, s[100:101] offset:128
	global_load_dwordx4 v[112:115], v132, s[100:101] offset:192
	global_load_dwordx4 v[116:119], v132, s[100:101] offset:256
	global_load_dwordx4 v[120:123], v132, s[100:101] offset:320
	global_load_dwordx4 v[124:127], v132, s[100:101] offset:384
	global_load_dwordx4 v[128:131], v132, s[100:101] offset:448
	v_lshl_add_u32 v99, v179, 4, v177
	v_mul_u32_u24_e32 v99, 528, v99
	v_lshl_add_u32 v99, v178, 4, v99
	v_mad_u32_u24 v154, v182, s6, v99
	v_xor_b32_e32 v155, 1, v182
	v_mad_u32_u24 v155, v155, s6, v99
	ds_read_b128 v[82:85], v154 offset:0
	ds_read_b128 v[156:159], v155 offset:0
	ds_read_b128 v[86:89], v154 offset:64
	ds_read_b128 v[160:163], v155 offset:64
	ds_read_b128 v[90:93], v154 offset:128
	ds_read_b128 v[164:167], v155 offset:128
	ds_read_b128 v[94:97], v154 offset:192
	ds_read_b128 v[168:171], v155 offset:192
	s_waitcnt lgkmcnt(6)
	v_add_f32_e32 v38, v82, v156
	v_add_f32_e32 v39, v83, v157
	v_add_f32_e32 v36, v84, v158
	v_add_f32_e32 v37, v85, v159
	v_mul_f32_e32 v2, v38, v38
	v_fmac_f32_e32 v2, v39, v39
	v_fmac_f32_e32 v2, v36, v36
	v_fmac_f32_e32 v2, v37, v37
	s_waitcnt lgkmcnt(4)
	v_add_f32_e32 v34, v86, v160
	v_add_f32_e32 v35, v87, v161
	v_add_f32_e32 v32, v88, v162
	v_add_f32_e32 v33, v89, v163
	v_fmac_f32_e32 v2, v34, v34
	v_fmac_f32_e32 v2, v35, v35
	v_fmac_f32_e32 v2, v32, v32
	v_fmac_f32_e32 v2, v33, v33
	s_waitcnt lgkmcnt(2)
	v_add_f32_e32 v30, v90, v164
	v_add_f32_e32 v31, v91, v165
	v_add_f32_e32 v28, v92, v166
	v_add_f32_e32 v29, v93, v167
	v_fmac_f32_e32 v2, v30, v30
	v_fmac_f32_e32 v2, v31, v31
	v_fmac_f32_e32 v2, v28, v28
	v_fmac_f32_e32 v2, v29, v29
	s_waitcnt lgkmcnt(0)
	v_add_f32_e32 v26, v94, v168
	v_add_f32_e32 v27, v95, v169
	v_add_f32_e32 v24, v96, v170
	v_add_f32_e32 v25, v97, v171
	v_fmac_f32_e32 v2, v26, v26
	v_fmac_f32_e32 v2, v27, v27
	v_fmac_f32_e32 v2, v24, v24
	v_fmac_f32_e32 v2, v25, v25
	ds_read_b128 v[82:85], v154 offset:256
	ds_read_b128 v[156:159], v155 offset:256
	ds_read_b128 v[86:89], v154 offset:320
	ds_read_b128 v[160:163], v155 offset:320
	ds_read_b128 v[90:93], v154 offset:384
	ds_read_b128 v[164:167], v155 offset:384
	ds_read_b128 v[94:97], v154 offset:448
	ds_read_b128 v[168:171], v155 offset:448
	s_waitcnt lgkmcnt(6)
	v_add_f32_e32 v22, v82, v156
	v_add_f32_e32 v23, v83, v157
	v_add_f32_e32 v20, v84, v158
	v_add_f32_e32 v21, v85, v159
	v_fmac_f32_e32 v2, v22, v22
	v_fmac_f32_e32 v2, v23, v23
	v_fmac_f32_e32 v2, v20, v20
	v_fmac_f32_e32 v2, v21, v21
	s_waitcnt lgkmcnt(4)
	v_add_f32_e32 v18, v86, v160
	v_add_f32_e32 v19, v87, v161
	v_add_f32_e32 v16, v88, v162
	v_add_f32_e32 v17, v89, v163
	v_fmac_f32_e32 v2, v18, v18
	v_fmac_f32_e32 v2, v19, v19
	v_fmac_f32_e32 v2, v16, v16
	v_fmac_f32_e32 v2, v17, v17
	s_waitcnt lgkmcnt(2)
	v_add_f32_e32 v14, v90, v164
	v_add_f32_e32 v15, v91, v165
	v_add_f32_e32 v12, v92, v166
	v_add_f32_e32 v13, v93, v167
	v_fmac_f32_e32 v2, v14, v14
	v_fmac_f32_e32 v2, v15, v15
	v_fmac_f32_e32 v2, v12, v12
	v_fmac_f32_e32 v2, v13, v13
	s_waitcnt lgkmcnt(0)
	v_add_f32_e32 v8, v94, v168
	v_add_f32_e32 v9, v95, v169
	v_add_f32_e32 v6, v96, v170
	v_add_f32_e32 v7, v97, v171
	v_fmac_f32_e32 v2, v8, v8
	v_fmac_f32_e32 v2, v9, v9
	v_fmac_f32_e32 v2, v6, v6
	v_fmac_f32_e32 v2, v7, v7
	ds_bpermute_b32 v3, v176, v2
	s_load_dwordx2 s[10:11], s[44:45], 0x80
	v_lshlrev_b32_e32 v4, 3, v178
	v_mov_b32_e32 v5, v0
	s_mov_b32 s6, 0x18a10000
	s_waitcnt lgkmcnt(0)
	v_add_f32_e32 v2, v2, v3
	ds_bpermute_b32 v1, v1, v2
	s_add_u32 s10, s10, s14
	s_addc_u32 s11, s11, s15
	s_mov_b64 s[14:15], 0x18a10000
	v_lshlrev_b32_e32 v44, 4, v178
	s_waitcnt lgkmcnt(0)
	v_add_f32_e32 v1, v2, v1
	v_fmamk_f32 v1, v1, 0x3c000000, v234
	v_cmp_gt_f32_e32 vcc, s90, v1
	v_mul_f32_e32 v2, 0x4b800000, v1
	s_nop 0
	v_cndmask_b32_e32 v1, v1, v2, vcc
	v_rsq_f32_e32 v1, v1
	s_nop 0
	v_mul_f32_e32 v2, 0x45800000, v1
	v_cndmask_b32_e32 v1, v1, v2, vcc
	v_lshlrev_b32_e32 v2, 4, v179
	v_or3_b32 v2, v2, v177, v180
	v_ashrrev_i32_e32 v3, 31, v2
	v_lshlrev_b64 v[2:3], 11, v[2:3]
	v_lshl_add_u64 v[2:3], s[42:43], 0, v[2:3]
	v_lshl_add_u64 v[2:3], v[2:3], 0, s[30:31]
	v_lshl_add_u64 v[2:3], v[2:3], 0, v[4:5]
	v_add_co_u32_e32 v40, vcc, s6, v2
	v_lshl_add_u64 v[10:11], v[2:3], 0, s[14:15]
	s_nop 0
	v_addc_co_u32_e32 v41, vcc, 0, v3, vcc
	v_mul_f32_e32 v1, v227, v1
	v_mul_f32_e32 v38, v38, v1
	v_mul_f32_e32 v36, v36, v1
	v_mul_f32_e32 v34, v34, v1
	v_mul_f32_e32 v32, v32, v1
	v_mul_f32_e32 v30, v30, v1
	v_mul_f32_e32 v28, v28, v1
	v_mul_f32_e32 v26, v26, v1
	v_mul_f32_e32 v24, v24, v1
	v_mul_f32_e32 v22, v22, v1
	v_mul_f32_e32 v20, v20, v1
	v_mul_f32_e32 v18, v18, v1
	v_mul_f32_e32 v16, v16, v1
	v_mul_f32_e32 v14, v14, v1
	v_mul_f32_e32 v12, v12, v1
	s_waitcnt vmcnt(0)
	v_readfirstlane_b32 s101, v224
	v_mov_b32_e32 v42, v146
	v_mov_b32_e32 v43, v147
	v_mov_b32_e32 v2, v100
	v_mov_b32_e32 v3, v101
	v_mov_b32_e32 v4, v102
	v_mov_b32_e32 v5, v103
	v_mul_f32_e32 v2, v2, v38
	v_lshlrev_b32_e32 v38, 16, v42
	v_mul_f32_e32 v2, v2, v38
	v_mul_f32_e32 v38, v39, v1
	v_mul_f32_e32 v4, v4, v36
	v_lshlrev_b32_e32 v36, 16, v43
	v_mul_f32_e32 v3, v3, v38
	v_and_b32_e32 v38, 0xffff0000, v42
	v_mul_f32_e32 v4, v4, v36
	v_mul_f32_e32 v36, v37, v1
	v_mul_f32_e32 v3, v3, v38
	v_mul_f32_e32 v5, v5, v36
	v_and_b32_e32 v36, 0xffff0000, v43
	v_mul_f32_e32 v5, v5, v36
	s_nop 1
	v_cvt_pk_bf16_f32 v2, v2, v3
	s_nop 1
	v_cvt_pk_bf16_f32 v3, v4, v5
	global_store_dwordx2 v[40:41], v[2:3], off
	v_mov_b32_e32 v36, v148
	v_mov_b32_e32 v37, v149
	s_nop 0
	v_mov_b32_e32 v2, v104
	v_mov_b32_e32 v3, v105
	v_mov_b32_e32 v4, v106
	v_mov_b32_e32 v5, v107
	v_mul_f32_e32 v2, v2, v34
	v_lshlrev_b32_e32 v34, 16, v36
	v_mul_f32_e32 v2, v2, v34
	v_mul_f32_e32 v34, v35, v1
	v_mul_f32_e32 v4, v4, v32
	v_lshlrev_b32_e32 v32, 16, v37
	v_mul_f32_e32 v3, v3, v34
	v_and_b32_e32 v34, 0xffff0000, v36
	v_mul_f32_e32 v4, v4, v32
	v_mul_f32_e32 v32, v33, v1
	v_mul_f32_e32 v3, v3, v34
	v_mul_f32_e32 v5, v5, v32
	v_and_b32_e32 v32, 0xffff0000, v37
	v_mul_f32_e32 v5, v5, v32
	s_nop 1
	v_cvt_pk_bf16_f32 v2, v2, v3
	s_nop 1
	v_cvt_pk_bf16_f32 v3, v4, v5
	global_store_dwordx2 v[10:11], v[2:3], off offset:32
	v_mov_b32_e32 v32, v150
	v_mov_b32_e32 v33, v151
	s_nop 0
	v_mov_b32_e32 v2, v108
	v_mov_b32_e32 v3, v109
	v_mov_b32_e32 v4, v110
	v_mov_b32_e32 v5, v111
	v_mul_f32_e32 v2, v2, v30
	v_lshlrev_b32_e32 v30, 16, v32
	v_mul_f32_e32 v2, v2, v30
	v_mul_f32_e32 v30, v31, v1
	v_mul_f32_e32 v4, v4, v28
	v_lshlrev_b32_e32 v28, 16, v33
	v_mul_f32_e32 v3, v3, v30
	v_and_b32_e32 v30, 0xffff0000, v32
	v_mul_f32_e32 v4, v4, v28
	v_mul_f32_e32 v28, v29, v1
	v_mul_f32_e32 v3, v3, v30
	v_mul_f32_e32 v5, v5, v28
	v_and_b32_e32 v28, 0xffff0000, v33
	v_mul_f32_e32 v5, v5, v28
	s_nop 1
	v_cvt_pk_bf16_f32 v2, v2, v3
	s_nop 1
	v_cvt_pk_bf16_f32 v3, v4, v5
	global_store_dwordx2 v[10:11], v[2:3], off offset:64
	v_mov_b32_e32 v28, v152
	v_mov_b32_e32 v29, v153
	s_nop 0
	v_mov_b32_e32 v2, v112
	v_mov_b32_e32 v3, v113
	v_mov_b32_e32 v4, v114
	v_mov_b32_e32 v5, v115
	v_mul_f32_e32 v2, v2, v26
	v_lshlrev_b32_e32 v26, 16, v28
	v_mul_f32_e32 v2, v2, v26
	v_mul_f32_e32 v26, v27, v1
	v_mul_f32_e32 v4, v4, v24
	v_lshlrev_b32_e32 v24, 16, v29
	v_mul_f32_e32 v3, v3, v26
	v_and_b32_e32 v26, 0xffff0000, v28
	v_mul_f32_e32 v4, v4, v24
	v_mul_f32_e32 v24, v25, v1
	v_mul_f32_e32 v3, v3, v26
	v_mul_f32_e32 v5, v5, v24
	v_and_b32_e32 v24, 0xffff0000, v29
	v_mul_f32_e32 v5, v5, v24
	s_nop 1
	v_cvt_pk_bf16_f32 v2, v2, v3
	s_nop 1
	v_cvt_pk_bf16_f32 v3, v4, v5
	global_store_dwordx2 v[10:11], v[2:3], off offset:96
	v_mov_b32_e32 v24, v188
	v_mov_b32_e32 v25, v189
	s_nop 0
	v_mov_b32_e32 v2, v116
	v_mov_b32_e32 v3, v117
	v_mov_b32_e32 v4, v118
	v_mov_b32_e32 v5, v119
	v_mul_f32_e32 v2, v2, v22
	v_lshlrev_b32_e32 v22, 16, v24
	v_mul_f32_e32 v2, v2, v22
	v_mul_f32_e32 v22, v23, v1
	v_mul_f32_e32 v4, v4, v20
	v_lshlrev_b32_e32 v20, 16, v25
	v_mul_f32_e32 v3, v3, v22
	v_and_b32_e32 v22, 0xffff0000, v24
	v_mul_f32_e32 v4, v4, v20
	v_mul_f32_e32 v20, v21, v1
	v_mul_f32_e32 v3, v3, v22
	v_mul_f32_e32 v5, v5, v20
	v_and_b32_e32 v20, 0xffff0000, v25
	v_mul_f32_e32 v5, v5, v20
	s_nop 1
	v_cvt_pk_bf16_f32 v2, v2, v3
	s_nop 1
	v_cvt_pk_bf16_f32 v3, v4, v5
	global_store_dwordx2 v[10:11], v[2:3], off offset:128
	v_mov_b32_e32 v20, v190
	v_mov_b32_e32 v21, v191
	s_nop 0
	v_mov_b32_e32 v2, v120
	v_mov_b32_e32 v3, v121
	v_mov_b32_e32 v4, v122
	v_mov_b32_e32 v5, v123
	v_mul_f32_e32 v2, v2, v18
	v_lshlrev_b32_e32 v18, 16, v20
	v_mul_f32_e32 v2, v2, v18
	v_mul_f32_e32 v18, v19, v1
	v_mul_f32_e32 v4, v4, v16
	v_lshlrev_b32_e32 v16, 16, v21
	v_mul_f32_e32 v3, v3, v18
	v_and_b32_e32 v18, 0xffff0000, v20
	v_mul_f32_e32 v4, v4, v16
	v_mul_f32_e32 v16, v17, v1
	v_mul_f32_e32 v3, v3, v18
	v_mul_f32_e32 v5, v5, v16
	v_and_b32_e32 v16, 0xffff0000, v21
	v_mul_f32_e32 v5, v5, v16
	s_nop 1
	v_cvt_pk_bf16_f32 v2, v2, v3
	s_nop 1
	v_cvt_pk_bf16_f32 v3, v4, v5
	global_store_dwordx2 v[10:11], v[2:3], off offset:160
	v_mov_b32_e32 v16, v192
	v_mov_b32_e32 v17, v193
	s_nop 0
	v_mov_b32_e32 v2, v124
	v_mov_b32_e32 v3, v125
	v_mov_b32_e32 v4, v126
	v_mov_b32_e32 v5, v127
	v_mul_f32_e32 v2, v2, v14
	v_lshlrev_b32_e32 v14, 16, v16
	v_mul_f32_e32 v2, v2, v14
	v_mul_f32_e32 v14, v15, v1
	v_mul_f32_e32 v4, v4, v12
	v_lshlrev_b32_e32 v12, 16, v17
	v_mul_f32_e32 v3, v3, v14
	v_and_b32_e32 v14, 0xffff0000, v16
	v_mul_f32_e32 v4, v4, v12
	v_mul_f32_e32 v12, v13, v1
	v_mul_f32_e32 v3, v3, v14
	v_mul_f32_e32 v5, v5, v12
	v_and_b32_e32 v12, 0xffff0000, v17
	v_mul_f32_e32 v5, v5, v12
	s_nop 1
	v_cvt_pk_bf16_f32 v2, v2, v3
	s_nop 1
	v_cvt_pk_bf16_f32 v3, v4, v5
	global_store_dwordx2 v[10:11], v[2:3], off offset:192
	v_mov_b32_e32 v2, v194
	v_mov_b32_e32 v3, v195
	s_nop 0
	v_mov_b32_e32 v12, v128
	v_mov_b32_e32 v13, v129
	v_mov_b32_e32 v14, v130
	v_mov_b32_e32 v15, v131
	v_mul_f32_e32 v4, v8, v1
	v_lshlrev_b32_e32 v5, 16, v2
	v_mul_f32_e32 v4, v4, v12
	v_mul_f32_e32 v4, v4, v5
	v_mul_f32_e32 v5, v9, v1
	v_mul_f32_e32 v5, v5, v13
	v_and_b32_e32 v2, 0xffff0000, v2
	v_mul_f32_e32 v2, v5, v2
	v_mul_f32_e32 v5, v6, v1
	v_mul_f32_e32 v1, v7, v1
	v_mul_f32_e32 v5, v5, v14
	v_lshlrev_b32_e32 v6, 16, v3
	v_mul_f32_e32 v1, v1, v15
	v_and_b32_e32 v3, 0xffff0000, v3
	v_mul_f32_e32 v5, v5, v6
	v_mul_f32_e32 v1, v1, v3
	s_nop 1
	v_cvt_pk_bf16_f32 v2, v4, v2
	s_nop 1
	v_cvt_pk_bf16_f32 v3, v5, v1
	global_store_dwordx2 v[10:11], v[2:3], off offset:224
	s_barrier
